# MLA attention: triple-buffered K/V LDS, staging one tile ahead (rotated loop), 2 barriers per tile with waves 4-7 one barrier phase behind waves 0-3 (MFMA/VALU overlap across halves)
# baseline (speedup 1.0000x reference)
.LBB0_554:
	s_or_b64 exec, exec, s[12:13]
	s_lshl_b32 s12, s57, 20
	v_ashrrev_i32_e32 v16, 3, v8
	s_add_u32 s12, s45, s12
	v_ashrrev_i32_e32 v12, 3, v6
	v_ashrrev_i32_e32 v17, 31, v16
	s_addc_u32 s13, s46, 0
	v_ashrrev_i32_e32 v13, 31, v12
	v_lshlrev_b64 v[18:19], 13, v[16:17]
	v_lshlrev_b32_e32 v0, 4, v6
	v_lshlrev_b64 v[14:15], 13, v[12:13]
	v_lshl_add_u64 v[18:19], s[12:13], 0, v[18:19]
	v_and_b32_e32 v0, 0x70, v0
	v_lshl_add_u64 v[14:15], s[12:13], 0, v[14:15]
	v_lshl_add_u64 v[174:175], v[18:19], 0, v[0:1]
	v_lshl_add_u64 v[172:173], v[14:15], 0, v[0:1]
	global_load_dwordx4 v[164:167], v[174:175], off
	global_load_dwordx4 v[168:171], v[172:173], off
	v_add_u32_e32 v186, v7, v3
	v_add_u32_e32 v17, 0, v0
	v_mul_lo_u32 v0, v186, 20
	s_movk_i32 s12, 0x150
	v_add_u32_e32 v187, v10, v9
	v_and_b32_e32 v13, 31, v6
	v_sub_u32_e32 v0, v6, v0
	v_mul_lo_u32 v6, v187, s12
	v_mul_lo_u32 v3, v186, s12
	v_add_u32_e32 v20, 0, v6
	v_mul_lo_u32 v6, v185, s12
	s_movk_i32 s12, 0x88
	v_add_u32_e32 v18, 0, v3
	v_mul_lo_u32 v3, v187, 20
	v_add_u32_e32 v22, 0, v6
	v_mul_lo_u32 v24, v12, s12
	v_mul_lo_u32 v16, v16, s12
	v_lshlrev_b32_e32 v6, 3, v0
	v_readlane_b32 s12, v253, 29
	v_sub_u32_e32 v3, v8, v3
	v_ashrrev_i32_e32 v7, 31, v6
	v_readlane_b32 s13, v253, 30
	s_mov_b32 s12, 64
	v_lshl_add_u64 v[176:177], v[6:7], 1, s[22:23]
	v_lshlrev_b32_e32 v6, 3, v3
	v_writelane_b32 v253, s12, 29
	v_lshlrev_b32_e32 v19, 4, v0
	v_lshlrev_b32_e32 v21, 4, v3
	v_lshlrev_b32_e32 v23, 4, v11
	v_ashrrev_i32_e32 v7, 31, v6
	v_mul_u32_u24_e32 v0, 0x150, v13
	v_lshl_add_u32 v25, v182, 3, 0
	v_mul_u32_u24_e32 v26, 0x88, v13
	v_writelane_b32 v253, s13, 30
	v_mov_b32_e32 v14, v1
	v_mov_b32_e32 v15, v1
	s_movk_i32 s12, 0x5400
	v_lshl_add_u64 v[178:179], v[6:7], 1, s[22:23]
	v_lshl_add_u64 v[180:181], v[4:5], 1, s[22:23]
	v_add3_u32 v188, 0, v0, v2
	v_mov_b32_e32 v0, v1
	v_mov_b32_e32 v2, v1
	v_mov_b32_e32 v3, v1
	v_mov_b32_e32 v4, v1
	v_mov_b32_e32 v5, v1
	v_mov_b32_e32 v6, v1
	v_mov_b32_e32 v7, v1
	v_mov_b32_e32 v8, v1
	v_mov_b32_e32 v9, v1
	v_mov_b32_e32 v10, v1
	v_mov_b32_e32 v11, v1
	v_mov_b32_e32 v12, v1
	v_mov_b32_e32 v13, v1
	v_add_u32_e32 v189, v18, v19
	v_add_u32_e32 v190, v20, v21
	v_add_u32_e32 v191, v22, v23
	s_waitcnt vmcnt(3)
	v_add3_u32 v192, v17, v24, s12
	v_add3_u32 v193, v17, v16, s12
	v_add_u32_e32 v194, v25, v26
	v_mov_b64_e32 v[30:31], v[14:15]
	v_mov_b64_e32 v[46:47], v[14:15]
	v_mov_b64_e32 v[62:63], v[14:15]
	v_mov_b64_e32 v[78:79], v[14:15]
	s_sub_i32 s57, 64, s33
	s_mov_b32 s58, 0
	v_mov_b32_e32 v195, 0xf149f2ca
	v_mov_b32_e32 v184, 0
	v_mov_b64_e32 v[28:29], v[12:13]
	v_mov_b64_e32 v[26:27], v[10:11]
	v_mov_b64_e32 v[24:25], v[8:9]
	v_mov_b64_e32 v[22:23], v[6:7]
	v_mov_b64_e32 v[20:21], v[4:5]
	v_mov_b64_e32 v[18:19], v[2:3]
	v_mov_b64_e32 v[16:17], v[0:1]
	v_mov_b64_e32 v[44:45], v[12:13]
	v_mov_b64_e32 v[42:43], v[10:11]
	v_mov_b64_e32 v[40:41], v[8:9]
	v_mov_b64_e32 v[38:39], v[6:7]
	v_mov_b64_e32 v[36:37], v[4:5]
	v_mov_b64_e32 v[34:35], v[2:3]
	v_mov_b64_e32 v[32:33], v[0:1]
	v_mov_b64_e32 v[60:61], v[12:13]
	v_mov_b64_e32 v[58:59], v[10:11]
	v_mov_b64_e32 v[56:57], v[8:9]
	v_mov_b64_e32 v[54:55], v[6:7]
	v_mov_b64_e32 v[52:53], v[4:5]
	v_mov_b64_e32 v[50:51], v[2:3]
	v_mov_b64_e32 v[48:49], v[0:1]
	v_mov_b64_e32 v[76:77], v[12:13]
	v_mov_b64_e32 v[74:75], v[10:11]
	v_mov_b64_e32 v[72:73], v[8:9]
	v_mov_b64_e32 v[70:71], v[6:7]
	v_mov_b64_e32 v[68:69], v[4:5]
	v_mov_b64_e32 v[66:67], v[2:3]
	v_mov_b64_e32 v[64:65], v[0:1]
	s_mov_b32 s98, 2
	v_add_u32_e32 v188, 0x13000, v188
	v_add_u32_e32 v194, 0x13000, v194
	s_branch .LBB0_556
.LBB0_555:
	s_or_b64 exec, exec, s[22:23]
	s_add_i32 s98, s98, 1
	s_cmp_eq_u32 s98, 3
	s_cselect_b32 s98, 0, s98
	s_mov_b32 s99, 0x9800
	s_cselect_b32 s99, 0xfffed000, s99
	v_add_u32_e32 v188, s99, v188
	v_add_u32_e32 v194, s99, v194
	s_cmp_eq_u32 s98, 2
	s_mov_b32 s99, 0x9800
	s_cselect_b32 s99, 0xfffed000, s99
	v_add_u32_e32 v189, s99, v189
	v_add_u32_e32 v190, s99, v190
	v_add_u32_e32 v191, s99, v191
	v_add_u32_e32 v192, s99, v192
	v_add_u32_e32 v193, s99, v193
	v_readlane_b32 s12, v253, 29
	v_readlane_b32 s13, v253, 30
	s_add_i32 s12, s12, 64
	s_add_i32 s58, s58, 1
	v_writelane_b32 v253, s12, 29
	s_add_i32 s99, s57, 1
	s_cmp_eq_u32 s99, s58
	s_nop 0
	v_writelane_b32 v253, s13, 30
	s_cbranch_scc1 .LBB0_573
.LBB0_556:
	s_cmp_eq_u32 s58, s57
	s_cbranch_scc1 .LBB0_566
	s_and_saveexec_b64 s[12:13], s[6:7]
	s_cbranch_execnz .LBB0_568
	s_or_b64 exec, exec, s[12:13]
	s_and_saveexec_b64 s[12:13], s[8:9]
	s_cbranch_execnz .LBB0_569

.LBB0_566:
	s_cmp_lg_u32 s58, 0
	s_cbranch_scc1 .Llag_go_556
	v_readfirstlane_b32 s99, v201
	s_nop 3
	s_cmpk_lt_u32 s99, 0x100
	s_cbranch_scc1 .Llag_first_556
	s_barrier

.Llag_go_556:
	s_and_saveexec_b64 s[22:23], vcc
	s_cbranch_execz .Llag_skipy_556
	ds_read_b128 v[196:199], v188
	ds_read_b128 v[202:205], v188 offset:32
	ds_read_b128 v[206:209], v188 offset:64
	ds_read_b128 v[210:213], v188 offset:96
	ds_read_b128 v[220:223], v188 offset:128
	ds_read_b128 v[224:227], v188 offset:160
	ds_read_b128 v[2:5], v188 offset:192
	ds_read_b128 v[6:9], v188 offset:224
	s_waitcnt lgkmcnt(7)
	v_mfma_f32_32x32x16_bf16 v[96:111], v[196:199], v[148:151], 0
	ds_read_b128 v[196:199], v188 offset:256
	s_waitcnt lgkmcnt(7)
	v_mfma_f32_32x32x16_bf16 v[96:111], v[202:205], v[144:147], v[96:111]
	ds_read_b128 v[202:205], v188 offset:288
	s_waitcnt lgkmcnt(7)
	v_mfma_f32_32x32x16_bf16 v[96:111], v[206:209], v[140:143], v[96:111]
	ds_read_b128 v[206:209], v188 offset:10752
	s_waitcnt lgkmcnt(7)
	v_mfma_f32_32x32x16_bf16 v[96:111], v[210:213], v[136:139], v[96:111]
	ds_read_b128 v[210:213], v188 offset:10784
	s_waitcnt lgkmcnt(7)
	v_mfma_f32_32x32x16_bf16 v[96:111], v[220:223], v[132:135], v[96:111]
	ds_read_b128 v[220:223], v188 offset:10816
	s_waitcnt lgkmcnt(7)
	v_mfma_f32_32x32x16_bf16 v[96:111], v[224:227], v[128:131], v[96:111]
	ds_read_b128 v[224:227], v188 offset:10848
	s_waitcnt lgkmcnt(7)
	v_mfma_f32_32x32x16_bf16 v[96:111], v[2:5], v[124:127], v[96:111]
	ds_read_b128 v[2:5], v188 offset:10880
	s_waitcnt lgkmcnt(7)
	v_mfma_f32_32x32x16_bf16 v[96:111], v[6:9], v[120:123], v[96:111]
	ds_read_b128 v[6:9], v188 offset:10912
	s_waitcnt lgkmcnt(7)
	v_mfma_f32_32x32x16_bf16 v[96:111], v[196:199], v[116:119], v[96:111]
	ds_read_b128 v[196:199], v188 offset:10944
	s_waitcnt lgkmcnt(7)
	v_mfma_f32_32x32x16_bf16 v[96:111], v[202:205], v[112:115], v[96:111]
	ds_read_b128 v[202:205], v188 offset:10976
	s_waitcnt lgkmcnt(7)
	v_mfma_f32_32x32x16_bf16 v[80:95], v[206:209], v[148:151], 0
	ds_read_b128 v[206:209], v188 offset:11008
	s_waitcnt lgkmcnt(7)
	v_mfma_f32_32x32x16_bf16 v[80:95], v[210:213], v[144:147], v[80:95]
	ds_read_b128 v[210:213], v188 offset:11040
	s_waitcnt lgkmcnt(7)
	v_mfma_f32_32x32x16_bf16 v[80:95], v[220:223], v[140:143], v[80:95]
	s_waitcnt lgkmcnt(6)
	v_mfma_f32_32x32x16_bf16 v[80:95], v[224:227], v[136:139], v[80:95]
	s_waitcnt lgkmcnt(5)
	v_mfma_f32_32x32x16_bf16 v[80:95], v[2:5], v[132:135], v[80:95]
	s_waitcnt lgkmcnt(4)
	v_mfma_f32_32x32x16_bf16 v[80:95], v[6:9], v[128:131], v[80:95]
	s_waitcnt lgkmcnt(3)
	v_mfma_f32_32x32x16_bf16 v[80:95], v[196:199], v[124:127], v[80:95]
	v_max_f32_e32 v0, v97, v97
	v_max_f32_e32 v10, v96, v96
	v_max_f32_e32 v0, v10, v0
	v_max3_f32 v0, v0, v98, v99
	v_max3_f32 v0, v0, v100, v101
	v_max3_f32 v0, v0, v102, v103
	v_max3_f32 v0, v0, v104, v105
	v_max3_f32 v0, v0, v106, v107
	v_max3_f32 v0, v0, v108, v109
	v_max3_f32 v0, v0, v110, v111
	v_and_b32_e32 v3, 64, v218
	v_xor_b32_e32 v2, 32, v218
	v_add_u32_e32 v3, 64, v3
	v_cmp_lt_i32_e64 s[12:13], v2, v3
	s_nop 1
	v_cndmask_b32_e64 v2, v218, v2, s[12:13]
	s_waitcnt lgkmcnt(2)
	v_mfma_f32_32x32x16_bf16 v[80:95], v[202:205], v[120:123], v[80:95]
	s_waitcnt lgkmcnt(1)
	v_mfma_f32_32x32x16_bf16 v[80:95], v[206:209], v[116:119], v[80:95]
	s_waitcnt lgkmcnt(0)
	v_mfma_f32_32x32x16_bf16 v[80:95], v[210:213], v[112:115], v[80:95]
	v_lshlrev_b32_e32 v2, 2, v2
	s_nop 10
	v_max3_f32 v0, v0, v80, v81
	v_max3_f32 v0, v0, v82, v83
	v_max3_f32 v0, v0, v84, v85
	v_max3_f32 v0, v0, v86, v87
	v_max3_f32 v0, v0, v88, v89
	v_max3_f32 v0, v0, v90, v91
	v_max3_f32 v0, v0, v92, v93
	v_max3_f32 v0, v0, v94, v95
	ds_bpermute_b32 v2, v2, v0
	s_waitcnt lgkmcnt(0)
	v_max3_f32 v0, v195, v0, v2
	v_sub_f32 v4, v97, v0
	v_sub_f32 v3, v96, v0
	v_sub_f32 v5, v100, v0
	v_sub_f32_e32 v2, v195, v0
	v_exp_f32_e32 v8, v4
	v_sub_f32 v4, v98, v0
	v_exp_f32_e32 v3, v3
	v_exp_f32_e32 v9, v4
	v_sub_f32 v4, v99, v0
	v_exp_f32_e32 v11, v5
	v_exp_f32_e32 v10, v4
	v_add_f32 v4, v1, v3
	v_sub_f32 v5, v101, v0
	v_exp_f32_e32 v2, v2
	v_add_f32 v4, v4, v8
	v_exp_f32_e32 v12, v5
	v_add_f32 v4, v4, v9
	v_sub_f32 v5, v102, v0
	v_cvt_pk_bf16_f32 v8, v3, v8
	v_add_f32 v4, v4, v10
	v_exp_f32_e32 v13, v5
	v_add_f32 v4, v4, v11
	v_sub_f32 v5, v103, v0
	v_add_u32_e32 v3, 0x6000, v194
	v_add_f32 v4, v4, v12
	v_exp_f32_e32 v14, v5
	v_add_f32 v4, v4, v13
	v_cvt_pk_bf16_f32 v9, v9, v10
	v_add_f32 v96, v4, v14
	v_sub_f32 v4, v104, v0
	v_add_u32_e32 v104, 0x5000, v194
	v_exp_f32_e32 v97, v4
	v_sub_f32 v4, v105, v0
	v_cvt_pk_bf16_f32 v10, v11, v12
	v_exp_f32_e32 v98, v4
	v_sub_f32 v4, v106, v0
	v_cvt_pk_bf16_f32 v11, v13, v14
	v_exp_f32_e32 v99, v4
	v_sub_f32 v4, v107, v0
	ds_read2_b64 v[12:15], v3 offset0:160 offset1:162
	v_exp_f32_e32 v100, v4
	v_sub_f32 v4, v108, v0
	s_barrier
	v_pk_mul_f32 v[64:65], v[64:65], v[2:3] op_sel_hi:[1,0]
	v_pk_mul_f32 v[66:67], v[66:67], v[2:3] op_sel_hi:[1,0]
	v_pk_mul_f32 v[68:69], v[68:69], v[2:3] op_sel_hi:[1,0]
	s_nop 0
	v_exp_f32_e32 v101, v4
	v_sub_f32 v4, v109, v0
	v_pk_mul_f32 v[70:71], v[70:71], v[2:3] op_sel_hi:[1,0]
	v_pk_mul_f32 v[72:73], v[72:73], v[2:3] op_sel_hi:[1,0]
	s_nop 0
	v_exp_f32_e32 v102, v4
	v_sub_f32 v4, v110, v0
	v_pk_mul_f32 v[74:75], v[74:75], v[2:3] op_sel_hi:[1,0]
	v_pk_mul_f32 v[76:77], v[76:77], v[2:3] op_sel_hi:[1,0]
	v_pk_mul_f32 v[78:79], v[78:79], v[2:3] op_sel_hi:[1,0]
	s_nop 0
	v_exp_f32_e32 v103, v4
	ds_read2_b64 v[4:7], v104 offset0:128 offset1:130
	v_add_u32_e32 v105, 0x7000, v194
	s_waitcnt lgkmcnt(0)
	v_mfma_f32_32x32x16_bf16 v[64:79], v[4:7], v[8:11], v[64:79]
	ds_read2_b64 v[4:7], v105 offset0:192 offset1:194
	v_pk_mul_f32 v[48:49], v[48:49], v[2:3] op_sel_hi:[1,0]
	v_pk_mul_f32 v[50:51], v[50:51], v[2:3] op_sel_hi:[1,0]
	v_pk_mul_f32 v[52:53], v[52:53], v[2:3] op_sel_hi:[1,0]
	v_pk_mul_f32 v[54:55], v[54:55], v[2:3] op_sel_hi:[1,0]
	v_pk_mul_f32 v[56:57], v[56:57], v[2:3] op_sel_hi:[1,0]
	v_pk_mul_f32 v[58:59], v[58:59], v[2:3] op_sel_hi:[1,0]
	v_pk_mul_f32 v[60:61], v[60:61], v[2:3] op_sel_hi:[1,0]
	v_pk_mul_f32 v[62:63], v[62:63], v[2:3] op_sel_hi:[1,0]
	v_add_u32_e32 v106, 0x8000, v194
	v_mfma_f32_32x32x16_bf16 v[48:63], v[12:15], v[8:11], v[48:63]
	ds_read2_b64 v[12:15], v106 offset0:224 offset1:226
	v_pk_mul_f32 v[32:33], v[32:33], v[2:3] op_sel_hi:[1,0]
	v_pk_mul_f32 v[34:35], v[34:35], v[2:3] op_sel_hi:[1,0]
	v_pk_mul_f32 v[36:37], v[36:37], v[2:3] op_sel_hi:[1,0]
	v_pk_mul_f32 v[38:39], v[38:39], v[2:3] op_sel_hi:[1,0]
	v_pk_mul_f32 v[40:41], v[40:41], v[2:3] op_sel_hi:[1,0]
	v_pk_mul_f32 v[42:43], v[42:43], v[2:3] op_sel_hi:[1,0]
	v_pk_mul_f32 v[44:45], v[44:45], v[2:3] op_sel_hi:[1,0]
	v_pk_mul_f32 v[46:47], v[46:47], v[2:3] op_sel_hi:[1,0]
	v_pk_mul_f32 v[16:17], v[16:17], v[2:3] op_sel_hi:[1,0]
	v_pk_mul_f32 v[18:19], v[18:19], v[2:3] op_sel_hi:[1,0]
	v_pk_mul_f32 v[20:21], v[20:21], v[2:3] op_sel_hi:[1,0]
	s_waitcnt lgkmcnt(1)
	v_mfma_f32_32x32x16_bf16 v[32:47], v[4:7], v[8:11], v[32:47]
	ds_read2_b64 v[4:7], v104 offset0:132 offset1:134
	v_pk_mul_f32 v[22:23], v[22:23], v[2:3] op_sel_hi:[1,0]
	v_pk_mul_f32 v[24:25], v[24:25], v[2:3] op_sel_hi:[1,0]
	v_pk_mul_f32 v[26:27], v[26:27], v[2:3] op_sel_hi:[1,0]
	v_pk_mul_f32 v[28:29], v[28:29], v[2:3] op_sel_hi:[1,0]
	v_pk_mul_f32 v[30:31], v[30:31], v[2:3] op_sel_hi:[1,0]
	v_mov_b32_e32 v195, v0
	s_waitcnt lgkmcnt(1)
	v_mfma_f32_32x32x16_bf16 v[16:31], v[12:15], v[8:11], v[16:31]
	v_sub_f32 v8, v111, v0
	v_cvt_pk_bf16_f32 v9, v99, v100
	v_exp_f32_e32 v107, v8
	v_cvt_pk_bf16_f32 v8, v97, v98
	v_cvt_pk_bf16_f32 v10, v101, v102
	ds_read2_b64 v[12:15], v3 offset0:164 offset1:166
	v_cvt_pk_bf16_f32 v11, v103, v107
	s_waitcnt lgkmcnt(1)
	s_nop 0
	v_mfma_f32_32x32x16_bf16 v[64:79], v[4:7], v[8:11], v[64:79]
	v_add_f32 v4, v96, v97
	s_nop 0
	v_add_f32 v4, v4, v98
	s_nop 0
	v_add_f32 v4, v4, v99
	s_nop 0
	v_add_f32 v96, v4, v100
	v_sub_f32 v4, v80, v0
	s_waitcnt lgkmcnt(0)
	v_mfma_f32_32x32x16_bf16 v[48:63], v[12:15], v[8:11], v[48:63]
	v_exp_f32_e32 v80, v4
	ds_read2_b64 v[4:7], v105 offset0:196 offset1:198
	v_sub_f32 v12, v81, v0
	s_nop 0
	v_exp_f32_e32 v81, v12
	v_sub_f32 v12, v82, v0
	s_nop 0
	v_exp_f32_e32 v82, v12
	v_sub_f32 v12, v83, v0
	s_waitcnt lgkmcnt(0)
	v_mfma_f32_32x32x16_bf16 v[32:47], v[4:7], v[8:11], v[32:47]
	v_exp_f32_e32 v83, v12
	ds_read2_b64 v[12:15], v106 offset0:228 offset1:230
	v_sub_f32 v4, v84, v0
	s_nop 0
	v_exp_f32_e32 v84, v4
	v_sub_f32 v4, v85, v0
	s_nop 0
	v_exp_f32_e32 v85, v4
	v_sub_f32 v4, v86, v0
	s_waitcnt lgkmcnt(0)
	v_mfma_f32_32x32x16_bf16 v[16:31], v[12:15], v[8:11], v[16:31]
	v_exp_f32_e32 v86, v4
	ds_read2_b64 v[4:7], v104 offset0:136 offset1:138
	v_sub_f32 v8, v87, v0
	ds_read2_b64 v[12:15], v3 offset0:168 offset1:170
	v_exp_f32_e32 v87, v8
	v_cvt_pk_bf16_f32 v8, v80, v81
	v_cvt_pk_bf16_f32 v9, v82, v83
	v_cvt_pk_bf16_f32 v10, v84, v85
	v_cvt_pk_bf16_f32 v11, v86, v87
	s_waitcnt lgkmcnt(1)
	s_nop 0
	v_mfma_f32_32x32x16_bf16 v[64:79], v[4:7], v[8:11], v[64:79]
	v_add_f32 v4, v96, v101
	s_nop 0
	v_add_f32 v4, v4, v102
	s_nop 0
	v_add_f32 v4, v4, v103
	s_nop 0
	v_add_f32 v96, v4, v107
	v_sub_f32 v4, v88, v0
	s_waitcnt lgkmcnt(0)
	v_mfma_f32_32x32x16_bf16 v[48:63], v[12:15], v[8:11], v[48:63]
	v_exp_f32_e32 v88, v4
	ds_read2_b64 v[4:7], v105 offset0:200 offset1:202
	v_sub_f32 v12, v89, v0
	s_nop 0
	v_exp_f32_e32 v89, v12
	v_sub_f32 v12, v90, v0
	s_nop 0
	v_exp_f32_e32 v90, v12
	v_sub_f32 v12, v91, v0
	s_waitcnt lgkmcnt(0)
	v_mfma_f32_32x32x16_bf16 v[32:47], v[4:7], v[8:11], v[32:47]
	v_exp_f32_e32 v91, v12
	ds_read2_b64 v[12:15], v106 offset0:232 offset1:234
	v_sub_f32 v4, v92, v0
	s_nop 0
	v_exp_f32_e32 v92, v4
	v_sub_f32 v4, v93, v0
	s_nop 0
	v_exp_f32_e32 v93, v4
	v_sub_f32 v4, v94, v0
	s_waitcnt lgkmcnt(0)
	v_mfma_f32_32x32x16_bf16 v[16:31], v[12:15], v[8:11], v[16:31]
	v_exp_f32_e32 v94, v4
	ds_read2_b64 v[4:7], v104 offset0:140 offset1:142
	ds_read2_b64 v[12:15], v3 offset0:172 offset1:174
	v_sub_f32 v8, v95, v0
	v_cvt_pk_bf16_f32 v9, v90, v91
	v_exp_f32_e32 v95, v8
	v_cvt_pk_bf16_f32 v8, v88, v89
	v_cvt_pk_bf16_f32 v10, v92, v93
	v_add_f32 v3, v96, v80
	v_cvt_pk_bf16_f32 v11, v94, v95
	v_add_f32 v3, v3, v81
	s_nop 0
	v_add_f32 v3, v3, v82
	s_waitcnt lgkmcnt(1)
	v_mfma_f32_32x32x16_bf16 v[64:79], v[4:7], v[8:11], v[64:79]
	ds_read2_b64 v[4:7], v105 offset0:204 offset1:206
	v_add_f32 v3, v3, v83
	s_nop 0
	v_add_f32 v3, v3, v84
	s_nop 0
	v_add_f32 v3, v3, v85
	s_waitcnt lgkmcnt(1)
	v_mfma_f32_32x32x16_bf16 v[48:63], v[12:15], v[8:11], v[48:63]
	ds_read2_b64 v[12:15], v106 offset0:236 offset1:238
	v_add_f32 v3, v3, v86
	s_nop 0
	v_add_f32 v3, v3, v87
	s_nop 0
	v_add_f32 v3, v3, v88
	s_nop 0
	v_add_f32 v3, v3, v89
	s_waitcnt lgkmcnt(1)
	v_mfma_f32_32x32x16_bf16 v[32:47], v[4:7], v[8:11], v[32:47]
	v_add_f32 v3, v3, v90
	s_nop 0
	v_add_f32 v3, v3, v91
	s_nop 0
	v_add_f32 v3, v3, v92
	s_nop 0
	v_add_f32 v3, v3, v93
	s_waitcnt lgkmcnt(0)
	v_mfma_f32_32x32x16_bf16 v[16:31], v[12:15], v[8:11], v[16:31]
	v_add_f32 v3, v3, v94
	s_nop 0
	v_add_f32 v3, v3, v95
	s_nop 0
	v_fmac_f32_e32 v3, v184, v2
	v_mov_b32_e32 v184, v3
	s_branch .LBB0_555
.Llag_skipy_556:
	s_barrier
	s_branch .LBB0_555

.LBB0_573:
	v_readfirstlane_b32 s99, v201
	s_nop 3
	s_cmpk_ge_u32 s99, 0x100
	s_cbranch_scc1 .Llag_nof_556
	s_barrier

.LBB0_586:
	s_or_b64 exec, exec, s[26:27]
	s_mul_i32 s24, s33, 0x84000
	s_mul_hi_u32 s25, s33, 0x84000
	s_add_u32 s24, s51, s24
	s_addc_u32 s25, s52, s25
	v_ashrrev_i32_e32 v15, 3, v8
	v_mov_b64_e32 v[16:17], s[24:25]
	s_movk_i32 s26, 0x1080
	v_ashrrev_i32_e32 v20, 3, v10
	v_lshlrev_b32_e32 v0, 4, v8
	v_mad_i64_i32 v[18:19], s[24:25], v15, s26, v[16:17]
	v_mad_i64_i32 v[16:17], s[24:25], v20, s26, v[16:17]
	v_and_b32_e32 v0, 0x70, v0
	v_lshl_add_u64 v[16:17], v[16:17], 0, v[0:1]
	v_lshl_add_u64 v[18:19], v[18:19], 0, v[0:1]
	global_load_dwordx4 v[164:167], v[16:17], off
	global_load_dwordx4 v[168:171], v[18:19], off
	v_mad_i64_i32 v[16:17], s[24:25], v15, s26, 0
	v_mad_i64_i32 v[18:19], s[24:25], v20, s26, 0
	v_add_u32_e32 v23, v9, v3
	v_mul_lo_u32 v3, v23, 20
	s_movk_i32 s24, 0x150
	v_and_b32_e32 v21, 31, v8
	v_sub_u32_e32 v3, v8, v3
	v_mul_lo_u32 v8, v23, s24
	v_add_u32_e32 v26, v12, v11
	v_add_u32_e32 v24, 0, v8
	v_mul_lo_u32 v8, v26, 20
	v_sub_u32_e32 v10, v10, v8
	v_mul_lo_u32 v8, v26, s24
	v_add_u32_e32 v27, 0, v8
	v_mul_lo_u32 v8, v13, s24
	s_movk_i32 s24, 0x88
	v_mul_lo_u32 v31, v15, s24
	v_mul_lo_u32 v20, v20, s24
	s_add_u32 s24, s58, 0x1f44d000
	v_lshlrev_b32_e32 v25, 4, v3
	v_add_u32_e32 v29, 0, v8
	v_lshlrev_b32_e32 v8, 3, v3
	v_mul_u32_u24_e32 v3, 0x150, v21
	s_addc_u32 s25, s57, 0
	v_lshlrev_b32_e32 v28, 4, v10
	v_lshlrev_b32_e32 v10, 3, v10
	v_add3_u32 v185, 0, v3, v2
	v_mov_b64_e32 v[2:3], s[24:25]
	s_movk_i32 s57, 0x140
	v_ashrrev_i32_e32 v11, 31, v10
	v_mad_i64_i32 v[12:13], s[26:27], v23, s57, v[2:3]
	v_mad_i64_i32 v[2:3], s[26:27], v26, s57, v[2:3]
	v_lshl_add_u64 v[174:175], v[10:11], 1, v[2:3]
	v_lshl_add_u64 v[2:3], s[24:25], 0, v[6:7]
	v_lshl_add_u64 v[176:177], v[4:5], 1, v[2:3]
	v_mov_b32_e32 v2, 0x84000
	v_mad_u64_u32 v[178:179], s[24:25], s33, v2, v[18:19]
	v_mad_u64_u32 v[180:181], s[24:25], s33, v2, v[16:17]
	v_add_u32_e32 v22, 0, v0
	v_lshlrev_b32_e32 v30, 4, v14
	v_ashrrev_i32_e32 v9, 31, v8
	v_lshl_add_u32 v32, v182, 3, 0
	v_mul_u32_u24_e32 v21, 0x88, v21
	v_mov_b32_e32 v14, v1
	v_mov_b32_e32 v15, v1
	s_movk_i32 s24, 0x5400
	v_lshl_add_u64 v[172:173], v[8:9], 1, v[12:13]
	v_or_b32_e32 v178, v178, v0
	v_or_b32_e32 v180, v180, v0
	v_mov_b32_e32 v0, v1
	v_mov_b32_e32 v2, v1
	v_mov_b32_e32 v3, v1
	v_mov_b32_e32 v4, v1
	v_mov_b32_e32 v5, v1
	v_mov_b32_e32 v6, v1
	v_mov_b32_e32 v7, v1
	v_mov_b32_e32 v8, v1
	v_mov_b32_e32 v9, v1
	v_mov_b32_e32 v10, v1
	v_mov_b32_e32 v11, v1
	v_mov_b32_e32 v12, v1
	v_mov_b32_e32 v13, v1
	v_add_u32_e32 v186, v24, v25
	v_add_u32_e32 v187, v27, v28
	v_add_u32_e32 v188, v29, v30
	v_add3_u32 v189, v22, v31, s24
	v_add3_u32 v190, v22, v20, s24
	v_add_u32_e32 v191, v32, v21
	v_mov_b64_e32 v[30:31], v[14:15]
	v_mov_b64_e32 v[46:47], v[14:15]
	v_mov_b64_e32 v[62:63], v[14:15]
	v_mov_b64_e32 v[78:79], v[14:15]
	s_mov_b32 s26, 0
	s_waitcnt vmcnt(3)
	v_mov_b32_e32 v192, 0xf149f2ca
	v_mov_b32_e32 v184, 0
	v_mov_b64_e32 v[28:29], v[12:13]
	v_mov_b64_e32 v[26:27], v[10:11]
	v_mov_b64_e32 v[24:25], v[8:9]
	v_mov_b64_e32 v[22:23], v[6:7]
	v_mov_b64_e32 v[20:21], v[4:5]
	v_mov_b64_e32 v[18:19], v[2:3]
	v_mov_b64_e32 v[16:17], v[0:1]
	v_mov_b64_e32 v[44:45], v[12:13]
	v_mov_b64_e32 v[42:43], v[10:11]
	v_mov_b64_e32 v[40:41], v[8:9]
	v_mov_b64_e32 v[38:39], v[6:7]
	v_mov_b64_e32 v[36:37], v[4:5]
	v_mov_b64_e32 v[34:35], v[2:3]
	v_mov_b64_e32 v[32:33], v[0:1]
	v_mov_b64_e32 v[60:61], v[12:13]
	v_mov_b64_e32 v[58:59], v[10:11]
	v_mov_b64_e32 v[56:57], v[8:9]
	v_mov_b64_e32 v[54:55], v[6:7]
	v_mov_b64_e32 v[52:53], v[4:5]
	v_mov_b64_e32 v[50:51], v[2:3]
	v_mov_b64_e32 v[48:49], v[0:1]
	v_mov_b64_e32 v[76:77], v[12:13]
	v_mov_b64_e32 v[74:75], v[10:11]
	v_mov_b64_e32 v[72:73], v[8:9]
	v_mov_b64_e32 v[70:71], v[6:7]
	v_mov_b64_e32 v[68:69], v[4:5]
	v_mov_b64_e32 v[66:67], v[2:3]
	v_mov_b64_e32 v[64:65], v[0:1]
	s_mov_b32 s98, 2
	v_add_u32_e32 v185, 0x13000, v185
	v_add_u32_e32 v191, 0x13000, v191
	s_branch .LBB0_588
.LBB0_587:
	s_or_b64 exec, exec, s[24:25]
	s_add_i32 s98, s98, 1
	s_cmp_eq_u32 s98, 3
	s_cselect_b32 s98, 0, s98
	s_mov_b32 s99, 0x9800
	s_cselect_b32 s99, 0xfffed000, s99
	v_add_u32_e32 v185, s99, v185
	v_add_u32_e32 v191, s99, v191
	s_cmp_eq_u32 s98, 2
	s_mov_b32 s99, 0x9800
	s_cselect_b32 s99, 0xfffed000, s99
	v_add_u32_e32 v186, s99, v186
	v_add_u32_e32 v187, s99, v187
	v_add_u32_e32 v188, s99, v188
	v_add_u32_e32 v189, s99, v189
	v_add_u32_e32 v190, s99, v190
	s_mov_b64 s[24:25], 0x5000
	s_add_i32 s26, s26, 1
	v_lshl_add_u64 v[172:173], v[172:173], 0, s[24:25]
	v_lshl_add_u64 v[174:175], v[174:175], 0, s[24:25]
	v_lshl_add_u64 v[176:177], v[176:177], 0, s[24:25]
	s_mov_b64 s[24:25], 0x80
	v_lshl_add_u64 v[178:179], v[178:179], 0, s[24:25]
	s_cmp_eq_u32 s26, 34
	v_lshl_add_u64 v[180:181], v[180:181], 0, s[24:25]
	s_cbranch_scc1 .LBB0_604
.LBB0_588:
	s_cmp_eq_u32 s26, 33
	s_cbranch_scc1 .LBB0_598
	s_and_saveexec_b64 s[24:25], s[8:9]
	s_cbranch_execnz .LBB0_600
	s_or_b64 exec, exec, s[24:25]
	s_and_saveexec_b64 s[24:25], s[10:11]
	s_cbranch_execnz .LBB0_601

.LBB0_598:
	s_cmp_lg_u32 s26, 0
	s_cbranch_scc1 .Llag_go_588
	v_readfirstlane_b32 s99, v201
	s_nop 3
	s_cmpk_lt_u32 s99, 0x100
	s_cbranch_scc1 .Llag_first_588
	s_barrier

.Llag_go_588:
	s_and_saveexec_b64 s[24:25], s[6:7]
	s_cbranch_execz .Llag_skipy_588
	ds_read_b128 v[194:197], v185
	ds_read_b128 v[202:205], v185 offset:32
	ds_read_b128 v[206:209], v185 offset:64
	ds_read_b128 v[210:213], v185 offset:96
	ds_read_b128 v[220:223], v185 offset:128
	ds_read_b128 v[224:227], v185 offset:160
	ds_read_b128 v[2:5], v185 offset:192
	ds_read_b128 v[6:9], v185 offset:224
	s_waitcnt lgkmcnt(7)
	v_mfma_f32_32x32x16_bf16 v[96:111], v[194:197], v[148:151], 0
	ds_read_b128 v[194:197], v185 offset:256
	s_waitcnt lgkmcnt(7)
	v_mfma_f32_32x32x16_bf16 v[96:111], v[202:205], v[144:147], v[96:111]
	ds_read_b128 v[202:205], v185 offset:288
	s_waitcnt lgkmcnt(7)
	v_mfma_f32_32x32x16_bf16 v[96:111], v[206:209], v[140:143], v[96:111]
	ds_read_b128 v[206:209], v185 offset:10752
	s_waitcnt lgkmcnt(7)
	v_mfma_f32_32x32x16_bf16 v[96:111], v[210:213], v[136:139], v[96:111]
	ds_read_b128 v[210:213], v185 offset:10784
	s_waitcnt lgkmcnt(7)
	v_mfma_f32_32x32x16_bf16 v[96:111], v[220:223], v[132:135], v[96:111]
	ds_read_b128 v[220:223], v185 offset:10816
	s_waitcnt lgkmcnt(7)
	v_mfma_f32_32x32x16_bf16 v[96:111], v[224:227], v[128:131], v[96:111]
	ds_read_b128 v[224:227], v185 offset:10848
	s_waitcnt lgkmcnt(7)
	v_mfma_f32_32x32x16_bf16 v[96:111], v[2:5], v[124:127], v[96:111]
	ds_read_b128 v[2:5], v185 offset:10880
	s_waitcnt lgkmcnt(7)
	v_mfma_f32_32x32x16_bf16 v[96:111], v[6:9], v[120:123], v[96:111]
	ds_read_b128 v[6:9], v185 offset:10912
	s_waitcnt lgkmcnt(7)
	v_mfma_f32_32x32x16_bf16 v[96:111], v[194:197], v[116:119], v[96:111]
	ds_read_b128 v[194:197], v185 offset:10944
	s_waitcnt lgkmcnt(7)
	v_mfma_f32_32x32x16_bf16 v[96:111], v[202:205], v[112:115], v[96:111]
	ds_read_b128 v[202:205], v185 offset:10976
	s_waitcnt lgkmcnt(7)
	v_mfma_f32_32x32x16_bf16 v[80:95], v[206:209], v[148:151], 0
	ds_read_b128 v[206:209], v185 offset:11008
	s_waitcnt lgkmcnt(7)
	v_mfma_f32_32x32x16_bf16 v[80:95], v[210:213], v[144:147], v[80:95]
	ds_read_b128 v[210:213], v185 offset:11040
	s_waitcnt lgkmcnt(7)
	v_mfma_f32_32x32x16_bf16 v[80:95], v[220:223], v[140:143], v[80:95]
	s_waitcnt lgkmcnt(6)
	v_mfma_f32_32x32x16_bf16 v[80:95], v[224:227], v[136:139], v[80:95]
	s_waitcnt lgkmcnt(5)
	v_mfma_f32_32x32x16_bf16 v[80:95], v[2:5], v[132:135], v[80:95]
	s_waitcnt lgkmcnt(4)
	v_mfma_f32_32x32x16_bf16 v[80:95], v[6:9], v[128:131], v[80:95]
	s_waitcnt lgkmcnt(3)
	v_mfma_f32_32x32x16_bf16 v[80:95], v[194:197], v[124:127], v[80:95]
	v_max_f32_e32 v0, v97, v97
	v_max_f32_e32 v10, v96, v96
	v_max_f32_e32 v0, v10, v0
	v_max3_f32 v0, v0, v98, v99
	v_max3_f32 v0, v0, v100, v101
	v_max3_f32 v0, v0, v102, v103
	v_max3_f32 v0, v0, v104, v105
	v_max3_f32 v0, v0, v106, v107
	v_max3_f32 v0, v0, v108, v109
	v_max3_f32 v0, v0, v110, v111
	v_and_b32_e32 v3, 64, v218
	v_xor_b32_e32 v2, 32, v218
	v_add_u32_e32 v3, 64, v3
	v_cmp_lt_i32_e32 vcc, v2, v3
	s_nop 1
	v_cndmask_b32_e32 v2, v218, v2, vcc
	s_waitcnt lgkmcnt(2)
	v_mfma_f32_32x32x16_bf16 v[80:95], v[202:205], v[120:123], v[80:95]
	s_waitcnt lgkmcnt(1)
	v_mfma_f32_32x32x16_bf16 v[80:95], v[206:209], v[116:119], v[80:95]
	s_waitcnt lgkmcnt(0)
	v_mfma_f32_32x32x16_bf16 v[80:95], v[210:213], v[112:115], v[80:95]
	v_lshlrev_b32_e32 v2, 2, v2
	s_nop 10
	v_max3_f32 v0, v0, v80, v81
	v_max3_f32 v0, v0, v82, v83
	v_max3_f32 v0, v0, v84, v85
	v_max3_f32 v0, v0, v86, v87
	v_max3_f32 v0, v0, v88, v89
	v_max3_f32 v0, v0, v90, v91
	v_max3_f32 v0, v0, v92, v93
	v_max3_f32 v0, v0, v94, v95
	ds_bpermute_b32 v2, v2, v0
	s_waitcnt lgkmcnt(0)
	v_max3_f32 v0, v192, v0, v2
	v_sub_f32 v4, v97, v0
	v_sub_f32 v3, v96, v0
	v_sub_f32 v5, v100, v0
	v_sub_f32_e32 v2, v192, v0
	v_exp_f32_e32 v8, v4
	v_sub_f32 v4, v98, v0
	v_exp_f32_e32 v3, v3
	v_exp_f32_e32 v9, v4
	v_sub_f32 v4, v99, v0
	v_exp_f32_e32 v11, v5
	v_exp_f32_e32 v10, v4
	v_add_f32 v4, v1, v3
	v_sub_f32 v5, v101, v0
	v_exp_f32_e32 v2, v2
	v_add_f32 v4, v4, v8
	v_exp_f32_e32 v12, v5
	v_add_f32 v4, v4, v9
	v_sub_f32 v5, v102, v0
	v_cvt_pk_bf16_f32 v8, v3, v8
	v_add_f32 v4, v4, v10
	v_exp_f32_e32 v13, v5
	v_add_f32 v4, v4, v11
	v_sub_f32 v5, v103, v0
	v_add_u32_e32 v3, 0x6000, v191
	v_add_f32 v4, v4, v12
	v_exp_f32_e32 v14, v5
	v_add_f32 v4, v4, v13
	v_cvt_pk_bf16_f32 v9, v9, v10
	v_add_f32 v96, v4, v14
	v_sub_f32 v4, v104, v0
	v_add_u32_e32 v104, 0x5000, v191
	v_exp_f32_e32 v97, v4
	v_sub_f32 v4, v105, v0
	v_cvt_pk_bf16_f32 v10, v11, v12
	v_exp_f32_e32 v98, v4
	v_sub_f32 v4, v106, v0
	v_cvt_pk_bf16_f32 v11, v13, v14
	v_exp_f32_e32 v99, v4
	v_sub_f32 v4, v107, v0
	ds_read2_b64 v[12:15], v3 offset0:160 offset1:162
	v_exp_f32_e32 v100, v4
	v_sub_f32 v4, v108, v0
	s_barrier
	v_pk_mul_f32 v[64:65], v[64:65], v[2:3] op_sel_hi:[1,0]
	v_pk_mul_f32 v[66:67], v[66:67], v[2:3] op_sel_hi:[1,0]
	v_pk_mul_f32 v[68:69], v[68:69], v[2:3] op_sel_hi:[1,0]
	s_nop 0
	v_exp_f32_e32 v101, v4
	v_sub_f32 v4, v109, v0
	v_pk_mul_f32 v[70:71], v[70:71], v[2:3] op_sel_hi:[1,0]
	v_pk_mul_f32 v[72:73], v[72:73], v[2:3] op_sel_hi:[1,0]
	s_nop 0
	v_exp_f32_e32 v102, v4
	v_sub_f32 v4, v110, v0
	v_pk_mul_f32 v[74:75], v[74:75], v[2:3] op_sel_hi:[1,0]
	v_pk_mul_f32 v[76:77], v[76:77], v[2:3] op_sel_hi:[1,0]
	v_pk_mul_f32 v[78:79], v[78:79], v[2:3] op_sel_hi:[1,0]
	s_nop 0
	v_exp_f32_e32 v103, v4
	ds_read2_b64 v[4:7], v104 offset0:128 offset1:130
	v_add_u32_e32 v105, 0x7000, v191
	s_waitcnt lgkmcnt(0)
	v_mfma_f32_32x32x16_bf16 v[64:79], v[4:7], v[8:11], v[64:79]
	ds_read2_b64 v[4:7], v105 offset0:192 offset1:194
	v_pk_mul_f32 v[48:49], v[48:49], v[2:3] op_sel_hi:[1,0]
	v_pk_mul_f32 v[50:51], v[50:51], v[2:3] op_sel_hi:[1,0]
	v_pk_mul_f32 v[52:53], v[52:53], v[2:3] op_sel_hi:[1,0]
	v_pk_mul_f32 v[54:55], v[54:55], v[2:3] op_sel_hi:[1,0]
	v_pk_mul_f32 v[56:57], v[56:57], v[2:3] op_sel_hi:[1,0]
	v_pk_mul_f32 v[58:59], v[58:59], v[2:3] op_sel_hi:[1,0]
	v_pk_mul_f32 v[60:61], v[60:61], v[2:3] op_sel_hi:[1,0]
	v_pk_mul_f32 v[62:63], v[62:63], v[2:3] op_sel_hi:[1,0]
	v_add_u32_e32 v106, 0x8000, v191
	v_mfma_f32_32x32x16_bf16 v[48:63], v[12:15], v[8:11], v[48:63]
	ds_read2_b64 v[12:15], v106 offset0:224 offset1:226
	v_pk_mul_f32 v[32:33], v[32:33], v[2:3] op_sel_hi:[1,0]
	v_pk_mul_f32 v[34:35], v[34:35], v[2:3] op_sel_hi:[1,0]
	v_pk_mul_f32 v[36:37], v[36:37], v[2:3] op_sel_hi:[1,0]
	v_pk_mul_f32 v[38:39], v[38:39], v[2:3] op_sel_hi:[1,0]
	v_pk_mul_f32 v[40:41], v[40:41], v[2:3] op_sel_hi:[1,0]
	v_pk_mul_f32 v[42:43], v[42:43], v[2:3] op_sel_hi:[1,0]
	v_pk_mul_f32 v[44:45], v[44:45], v[2:3] op_sel_hi:[1,0]
	v_pk_mul_f32 v[46:47], v[46:47], v[2:3] op_sel_hi:[1,0]
	v_pk_mul_f32 v[16:17], v[16:17], v[2:3] op_sel_hi:[1,0]
	v_pk_mul_f32 v[18:19], v[18:19], v[2:3] op_sel_hi:[1,0]
	v_pk_mul_f32 v[20:21], v[20:21], v[2:3] op_sel_hi:[1,0]
	s_waitcnt lgkmcnt(1)
	v_mfma_f32_32x32x16_bf16 v[32:47], v[4:7], v[8:11], v[32:47]
	ds_read2_b64 v[4:7], v104 offset0:132 offset1:134
	v_pk_mul_f32 v[22:23], v[22:23], v[2:3] op_sel_hi:[1,0]
	v_pk_mul_f32 v[24:25], v[24:25], v[2:3] op_sel_hi:[1,0]
	v_pk_mul_f32 v[26:27], v[26:27], v[2:3] op_sel_hi:[1,0]
	v_pk_mul_f32 v[28:29], v[28:29], v[2:3] op_sel_hi:[1,0]
	v_pk_mul_f32 v[30:31], v[30:31], v[2:3] op_sel_hi:[1,0]
	v_mov_b32_e32 v192, v0
	s_waitcnt lgkmcnt(1)
	v_mfma_f32_32x32x16_bf16 v[16:31], v[12:15], v[8:11], v[16:31]
	v_sub_f32 v8, v111, v0
	v_cvt_pk_bf16_f32 v9, v99, v100
	v_exp_f32_e32 v107, v8
	v_cvt_pk_bf16_f32 v8, v97, v98
	v_cvt_pk_bf16_f32 v10, v101, v102
	ds_read2_b64 v[12:15], v3 offset0:164 offset1:166
	v_cvt_pk_bf16_f32 v11, v103, v107
	s_waitcnt lgkmcnt(1)
	s_nop 0
	v_mfma_f32_32x32x16_bf16 v[64:79], v[4:7], v[8:11], v[64:79]
	v_add_f32 v4, v96, v97
	s_nop 0
	v_add_f32 v4, v4, v98
	s_nop 0
	v_add_f32 v4, v4, v99
	s_nop 0
	v_add_f32 v96, v4, v100
	v_sub_f32 v4, v80, v0
	s_waitcnt lgkmcnt(0)
	v_mfma_f32_32x32x16_bf16 v[48:63], v[12:15], v[8:11], v[48:63]
	v_exp_f32_e32 v80, v4
	ds_read2_b64 v[4:7], v105 offset0:196 offset1:198
	v_sub_f32 v12, v81, v0
	s_nop 0
	v_exp_f32_e32 v81, v12
	v_sub_f32 v12, v82, v0
	s_nop 0
	v_exp_f32_e32 v82, v12
	v_sub_f32 v12, v83, v0
	s_waitcnt lgkmcnt(0)
	v_mfma_f32_32x32x16_bf16 v[32:47], v[4:7], v[8:11], v[32:47]
	v_exp_f32_e32 v83, v12
	ds_read2_b64 v[12:15], v106 offset0:228 offset1:230
	v_sub_f32 v4, v84, v0
	s_nop 0
	v_exp_f32_e32 v84, v4
	v_sub_f32 v4, v85, v0
	s_nop 0
	v_exp_f32_e32 v85, v4
	v_sub_f32 v4, v86, v0
	s_waitcnt lgkmcnt(0)
	v_mfma_f32_32x32x16_bf16 v[16:31], v[12:15], v[8:11], v[16:31]
	v_exp_f32_e32 v86, v4
	ds_read2_b64 v[4:7], v104 offset0:136 offset1:138
	v_sub_f32 v8, v87, v0
	ds_read2_b64 v[12:15], v3 offset0:168 offset1:170
	v_exp_f32_e32 v87, v8
	v_cvt_pk_bf16_f32 v8, v80, v81
	v_cvt_pk_bf16_f32 v9, v82, v83
	v_cvt_pk_bf16_f32 v10, v84, v85
	v_cvt_pk_bf16_f32 v11, v86, v87
	s_waitcnt lgkmcnt(1)
	s_nop 0
	v_mfma_f32_32x32x16_bf16 v[64:79], v[4:7], v[8:11], v[64:79]
	v_add_f32 v4, v96, v101
	s_nop 0
	v_add_f32 v4, v4, v102
	s_nop 0
	v_add_f32 v4, v4, v103
	s_nop 0
	v_add_f32 v96, v4, v107
	v_sub_f32 v4, v88, v0
	s_waitcnt lgkmcnt(0)
	v_mfma_f32_32x32x16_bf16 v[48:63], v[12:15], v[8:11], v[48:63]
	v_exp_f32_e32 v88, v4
	ds_read2_b64 v[4:7], v105 offset0:200 offset1:202
	v_sub_f32 v12, v89, v0
	s_nop 0
	v_exp_f32_e32 v89, v12
	v_sub_f32 v12, v90, v0
	s_nop 0
	v_exp_f32_e32 v90, v12
	v_sub_f32 v12, v91, v0
	s_waitcnt lgkmcnt(0)
	v_mfma_f32_32x32x16_bf16 v[32:47], v[4:7], v[8:11], v[32:47]
	v_exp_f32_e32 v91, v12
	ds_read2_b64 v[12:15], v106 offset0:232 offset1:234
	v_sub_f32 v4, v92, v0
	s_nop 0
	v_exp_f32_e32 v92, v4
	v_sub_f32 v4, v93, v0
	s_nop 0
	v_exp_f32_e32 v93, v4
	v_sub_f32 v4, v94, v0
	s_waitcnt lgkmcnt(0)
	v_mfma_f32_32x32x16_bf16 v[16:31], v[12:15], v[8:11], v[16:31]
	v_exp_f32_e32 v94, v4
	ds_read2_b64 v[4:7], v104 offset0:140 offset1:142
	ds_read2_b64 v[12:15], v3 offset0:172 offset1:174
	v_sub_f32 v8, v95, v0
	v_cvt_pk_bf16_f32 v9, v90, v91
	v_exp_f32_e32 v95, v8
	v_cvt_pk_bf16_f32 v8, v88, v89
	v_cvt_pk_bf16_f32 v10, v92, v93
	v_add_f32 v3, v96, v80
	v_cvt_pk_bf16_f32 v11, v94, v95
	v_add_f32 v3, v3, v81
	s_nop 0
	v_add_f32 v3, v3, v82
	s_waitcnt lgkmcnt(1)
	v_mfma_f32_32x32x16_bf16 v[64:79], v[4:7], v[8:11], v[64:79]
	ds_read2_b64 v[4:7], v105 offset0:204 offset1:206
	v_add_f32 v3, v3, v83
	s_nop 0
	v_add_f32 v3, v3, v84
	s_nop 0
	v_add_f32 v3, v3, v85
	s_waitcnt lgkmcnt(1)
	v_mfma_f32_32x32x16_bf16 v[48:63], v[12:15], v[8:11], v[48:63]
	ds_read2_b64 v[12:15], v106 offset0:236 offset1:238
	v_add_f32 v3, v3, v86
	s_nop 0
	v_add_f32 v3, v3, v87
	s_nop 0
	v_add_f32 v3, v3, v88
	s_nop 0
	v_add_f32 v3, v3, v89
	s_waitcnt lgkmcnt(1)
	v_mfma_f32_32x32x16_bf16 v[32:47], v[4:7], v[8:11], v[32:47]
	v_add_f32 v3, v3, v90
	s_nop 0
	v_add_f32 v3, v3, v91
	s_nop 0
	v_add_f32 v3, v3, v92
	s_nop 0
	v_add_f32 v3, v3, v93
	s_waitcnt lgkmcnt(0)
	v_mfma_f32_32x32x16_bf16 v[16:31], v[12:15], v[8:11], v[16:31]
	v_add_f32 v3, v3, v94
	s_nop 0
	v_add_f32 v3, v3, v95
	s_nop 0
	v_fmac_f32_e32 v3, v184, v2
	v_mov_b32_e32 v184, v3
	s_branch .LBB0_587
